# NA bias softmax: for the four unit-weight keys per block, masked probability taken as cndmask(exp,0,mask) and summed with v_add (bit-identical), one VALU fewer per element
# speedup vs baseline: 1.0274x; 1.0274x over previous
; template <int DQK, bool NA, bool SMAX, int LDV> ...
;     ...
;         if (NA && it >= 4) {
;           const int kr = rs + (it - 4);
;           const int ql = w * 32 + qt * 16 + fr, qr = r0 + (ql >> 6), qc = ql & 63;
;           const int rst = min(max(qr - 4, 0), 24);
;           const bool rowok = (kr >= rst) && (kr < rst + 8);
;           const int cst = min(max(qc - 8, 0), 48);
;           const int base = (kr - qr + 7) * 31 + 15 - qc;
;           float bv[4][4];
; #pragma unroll
;           for (int kt = 0; kt < 4; ++kt)
; #pragma unroll
;             for (int j = 0; j < 4; ++j) bv[kt][j] = rpbl[min(max(base + kt * 16 + fq * 4 + j, 0), 464)];
; #pragma unroll
;           for (int kt = 0; kt < 4; ++kt)
; #pragma unroll
;             for (int j = 0; j < 4; ++j) {
;               const int kc = kt * 16 + fq * 4 + j;
;               const float okf = (rowok && (kc >= cst) && (kc < cst + 16)) ? 1.f : 0.f;
;               const float pv = __builtin_amdgcn_exp2f(__builtin_fmaf(s[kt][qt][j], c1, bv[kt][j] - m0)) * okf;
;               s[kt][qt][j] = pv; sum += pv;
;             }
.LBB0_1069:
	s_andn2_b64 vcc, exec, s[26:27]
	s_cbranch_vccnz .LBB0_1071
	v_subrev_u32_e32 v0, 31, v208
	s_movk_i32 s101, 0x100
	v_lshl_add_u32 v211, v0, 2, s101
	ds_read_b32 v104, v211 offset:41728
	ds_read_b32 v105, v211 offset:41732
	ds_read_b32 v106, v211 offset:41736
	ds_read_b32 v107, v211 offset:41740
	ds_read_b32 v108, v211 offset:41792
	ds_read_b32 v109, v211 offset:41796
	ds_read_b32 v110, v211 offset:41800
	ds_read_b32 v111, v211 offset:41804
	ds_read_b32 v112, v211 offset:41856
	ds_read_b32 v113, v211 offset:41860
	ds_read_b32 v114, v211 offset:41864
	ds_read_b32 v115, v211 offset:41868
	ds_read_b32 v128, v211 offset:41920
	s_add_i32 s26, s19, s43
	s_add_i32 s26, s26, -4
	ds_read_b32 v129, v211 offset:41924
	v_cmp_ge_i32_e32 vcc, s26, v164
	v_cmp_lt_i32_e64 s[40:41], s26, v163
	s_waitcnt lgkmcnt(13)
	s_or_b64 s[26:27], s[40:41], vcc
	v_fmac_f32_e32 v104, 0x3e38aa3b, v144
	s_waitcnt lgkmcnt(12)
	s_or_b64 s[40:41], s[26:27], s[58:59]
	v_exp_f32_e32 v130, v104
	v_fmac_f32_e32 v105, 0x3e38aa3b, v145
	ds_read_b32 v2, v211 offset:41928
	ds_read_b32 v3, v211 offset:41932
	v_cndmask_b32_e64 v104, v130, 0, s[40:41]
	v_readlane_b32 s40, v248, 21
	v_exp_f32_e32 v131, v105
	v_readlane_b32 s41, v248, 22
	s_or_b64 s[40:41], s[26:27], s[40:41]
	s_waitcnt lgkmcnt(13)
	v_mov_b32_e32 v0, v104
	v_cndmask_b32_e64 v105, v131, 0, s[40:41]
	v_fmac_f32_e32 v106, 0x3e38aa3b, v146
	v_add_f32_e32 v0, v0, v105
	v_exp_f32_e32 v131, v106
	s_or_b64 s[40:41], s[26:27], s[52:53]
	s_waitcnt lgkmcnt(12)
	v_cndmask_b32_e64 v106, v131, 0, s[40:41]
	v_fmac_f32_e32 v107, 0x3e38aa3b, v147
	v_add_f32_e32 v0, v0, v106
	v_exp_f32_e32 v131, v107
	s_or_b64 s[40:41], s[26:27], s[54:55]
	s_waitcnt lgkmcnt(11)
	v_cndmask_b32_e64 v107, v131, 0, s[40:41]
	v_fmac_f32_e32 v108, 0x3e38aa3b, v140
	v_add_f32_e32 v0, v0, v107
	v_exp_f32_e32 v131, v108
	s_or_b64 s[40:41], s[26:27], s[56:57]
	s_waitcnt lgkmcnt(10)
	v_cndmask_b32_e64 v130, v165, 0, s[40:41]
	v_fmac_f32_e32 v109, 0x3e38aa3b, v141
	v_mul_f32_e32 v108, v130, v131
	v_fmac_f32_e32 v0, v130, v131
	v_exp_f32_e32 v131, v109
	s_or_b64 s[40:41], s[26:27], s[60:61]
	s_waitcnt lgkmcnt(9)
	v_cndmask_b32_e64 v130, v166, 0, s[40:41]
	v_fmac_f32_e32 v110, 0x3e38aa3b, v142
	v_mul_f32_e32 v109, v130, v131
	v_fmac_f32_e32 v0, v130, v131
	v_exp_f32_e32 v131, v110
	s_or_b64 s[40:41], s[26:27], s[50:51]
	s_waitcnt lgkmcnt(8)
	v_cndmask_b32_e64 v130, v168, 0, s[40:41]
	v_fmac_f32_e32 v111, 0x3e38aa3b, v143
	v_mul_f32_e32 v110, v130, v131
	v_fmac_f32_e32 v0, v130, v131
	v_exp_f32_e32 v131, v111
	s_or_b64 s[40:41], s[26:27], s[64:65]
	s_waitcnt lgkmcnt(7)
	v_cndmask_b32_e64 v130, v169, 0, s[40:41]
	v_fmac_f32_e32 v112, 0x3e38aa3b, v136
	v_mul_f32_e32 v111, v130, v131
	v_fmac_f32_e32 v0, v130, v131
	v_exp_f32_e32 v131, v112
	s_or_b64 s[40:41], s[26:27], s[66:67]
	s_waitcnt lgkmcnt(6)
	v_cndmask_b32_e64 v130, v170, 0, s[40:41]
	v_fmac_f32_e32 v113, 0x3e38aa3b, v137
	v_mul_f32_e32 v112, v130, v131
	v_fmac_f32_e32 v0, v130, v131
	v_exp_f32_e32 v131, v113
	s_or_b64 s[40:41], s[26:27], s[68:69]
	s_waitcnt lgkmcnt(5)
	v_cndmask_b32_e64 v130, v171, 0, s[40:41]
	v_fmac_f32_e32 v114, 0x3e38aa3b, v138
	v_mul_f32_e32 v113, v130, v131
	v_fmac_f32_e32 v0, v130, v131
	v_exp_f32_e32 v131, v114
	s_or_b64 s[40:41], s[26:27], s[70:71]
	s_waitcnt lgkmcnt(4)
	v_cndmask_b32_e64 v130, v172, 0, s[40:41]
	v_fmac_f32_e32 v115, 0x3e38aa3b, v139
	v_mul_f32_e32 v114, v130, v131
	v_fmac_f32_e32 v0, v130, v131
	v_exp_f32_e32 v131, v115
	s_or_b64 s[40:41], s[26:27], s[72:73]
	s_waitcnt lgkmcnt(3)
	v_cndmask_b32_e64 v130, v173, 0, s[40:41]
	v_fmac_f32_e32 v128, 0x3e38aa3b, v132
	v_mul_f32_e32 v115, v130, v131
	v_fmac_f32_e32 v0, v130, v131
	v_exp_f32_e32 v131, v128
	s_waitcnt lgkmcnt(2)
	v_cndmask_b32_e64 v130, v174, 0, s[26:27]
	v_fmac_f32_e32 v129, 0x3e38aa3b, v133
	s_waitcnt lgkmcnt(1)
	v_mul_f32_e32 v128, v130, v131
	v_fmac_f32_e32 v0, v130, v131
	v_exp_f32_e32 v131, v129
	v_fmac_f32_e32 v2, 0x3e38aa3b, v134
	s_waitcnt lgkmcnt(0)
	v_exp_f32_e32 v2, v2
	v_fmac_f32_e32 v3, 0x3e38aa3b, v135
	v_exp_f32_e32 v3, v3
	v_cndmask_b32_e64 v130, v175, 0, s[26:27]
	v_mul_f32_e32 v129, v130, v131
	v_fmac_f32_e32 v0, v130, v131
	v_cndmask_b32_e64 v131, v176, 0, s[26:27]
	v_mul_f32_e32 v130, v131, v2
	v_fmac_f32_e32 v0, v131, v2
	v_cndmask_b32_e64 v2, v177, 0, s[26:27]
	v_mul_f32_e32 v131, v2, v3
	v_fmac_f32_e32 v0, v2, v3

; template <int DQK, bool NA, bool SMAX, int LDV> ...
;     ...
;         if (NA && it >= 4) {
;           const int kr = rs + (it - 4);
;           const int ql = w * 32 + qt * 16 + fr, qr = r0 + (ql >> 6), qc = ql & 63;
;           const int rst = min(max(qr - 4, 0), 24);
;           const bool rowok = (kr >= rst) && (kr < rst + 8);
;           const int cst = min(max(qc - 8, 0), 48);
;           const int base = (kr - qr + 7) * 31 + 15 - qc;
;           float bv[4][4];
; #pragma unroll
;           for (int kt = 0; kt < 4; ++kt)
; #pragma unroll
;             for (int j = 0; j < 4; ++j) bv[kt][j] = rpbl[min(max(base + kt * 16 + fq * 4 + j, 0), 464)];
; #pragma unroll
;           for (int kt = 0; kt < 4; ++kt)
; #pragma unroll
;             for (int j = 0; j < 4; ++j) {
;               const int kc = kt * 16 + fq * 4 + j;
;               const float okf = (rowok && (kc >= cst) && (kc < cst + 16)) ? 1.f : 0.f;
;               const float pv = __builtin_amdgcn_exp2f(__builtin_fmaf(s[kt][qt][j], c1, bv[kt][j] - m0)) * okf;
;               s[kt][qt][j] = pv; sum += pv;
;             }
.LBB0_1073:
	s_andn2_b64 vcc, exec, s[0:1]
	s_cbranch_vccnz .LBB0_1075
	v_subrev_u32_e32 v2, 47, v208
	s_movk_i32 s101, 0x100
	v_lshl_add_u32 v211, v2, 2, s101
	ds_read_b32 v132, v211 offset:41728
	ds_read_b32 v133, v211 offset:41732
	ds_read_b32 v134, v211 offset:41736
	ds_read_b32 v135, v211 offset:41740
	ds_read_b32 v136, v211 offset:41792
	ds_read_b32 v137, v211 offset:41796
	ds_read_b32 v138, v211 offset:41800
	ds_read_b32 v139, v211 offset:41804
	ds_read_b32 v140, v211 offset:41856
	ds_read_b32 v141, v211 offset:41860
	ds_read_b32 v142, v211 offset:41864
	ds_read_b32 v143, v211 offset:41868
	ds_read_b32 v144, v211 offset:41920
	s_add_i32 s0, s19, s43
	s_waitcnt lgkmcnt(12)
	s_add_i32 s26, s0, -4
	ds_read_b32 v145, v211 offset:41924
	v_fmac_f32_e32 v132, 0x3e38aa3b, v124
	s_waitcnt lgkmcnt(12)
	v_cmp_ge_i32_e64 s[0:1], s26, v164
	v_cmp_lt_i32_e32 vcc, s26, v163
	v_exp_f32_e32 v124, v132
	v_fmac_f32_e32 v133, 0x3e38aa3b, v125
	s_or_b64 s[0:1], vcc, s[0:1]
	v_exp_f32_e32 v125, v133
	s_or_b64 s[26:27], s[0:1], s[82:83]
	ds_read_b32 v3, v211 offset:41928
	ds_read_b32 v147, v211 offset:41932
	v_cndmask_b32_e64 v132, v124, 0, s[26:27]
	s_or_b64 s[26:27], s[0:1], s[74:75]
	v_mov_b32_e32 v2, v132
	v_cndmask_b32_e64 v133, v125, 0, s[26:27]
	v_add_f32_e32 v2, v2, v133
	s_waitcnt lgkmcnt(13)
	v_fma_f32 v125, v126, s62, v134
	v_exp_f32_e32 v125, v125
	s_or_b64 s[26:27], s[0:1], s[76:77]
	v_cndmask_b32_e64 v134, v125, 0, s[26:27]
	s_or_b64 s[26:27], s[0:1], s[78:79]
	v_add_f32_e32 v2, v2, v134
	s_waitcnt lgkmcnt(12)
	v_fma_f32 v125, v127, s62, v135
	v_exp_f32_e32 v125, v125
	s_nop 0
	v_cndmask_b32_e64 v135, v125, 0, s[26:27]
	s_or_b64 s[26:27], s[0:1], s[80:81]
	s_waitcnt lgkmcnt(1)
	v_add_f32_e32 v2, v2, v135
	v_fma_f32 v125, v120, s62, v136
	v_exp_f32_e32 v120, v125
	v_cndmask_b32_e64 v124, v178, 0, s[26:27]
	s_or_b64 s[26:27], s[0:1], s[84:85]
	v_fmac_f32_e32 v3, 0x3e38aa3b, v102
	v_mul_f32_e32 v136, v124, v120
	v_fmac_f32_e32 v2, v124, v120
	v_fma_f32 v124, v121, s62, v137
	v_exp_f32_e32 v121, v124
	v_cndmask_b32_e64 v120, v179, 0, s[26:27]
	s_or_b64 s[26:27], s[0:1], s[86:87]
	v_exp_f32_e32 v3, v3
	v_mul_f32_e32 v137, v120, v121
	v_fmac_f32_e32 v2, v120, v121
	v_fma_f32 v121, v122, s62, v138
	v_exp_f32_e32 v121, v121
	v_cndmask_b32_e64 v120, v180, 0, s[26:27]
	s_or_b64 s[26:27], s[0:1], s[88:89]
	v_mul_f32_e32 v138, v120, v121
	v_fmac_f32_e32 v2, v120, v121
	v_fma_f32 v121, v123, s62, v139
	v_exp_f32_e32 v121, v121
	v_cndmask_b32_e64 v120, v181, 0, s[26:27]
	s_or_b64 s[26:27], s[0:1], s[90:91]
	v_mul_f32_e32 v139, v120, v121
	v_fmac_f32_e32 v2, v120, v121
	v_fma_f32 v121, v116, s62, v140
	v_exp_f32_e32 v116, v121
	v_cndmask_b32_e64 v120, v182, 0, s[26:27]
	s_or_b64 s[26:27], s[0:1], s[92:93]
	v_mul_f32_e32 v140, v120, v116
	v_fmac_f32_e32 v2, v120, v116
	v_fma_f32 v120, v117, s62, v141
	v_exp_f32_e32 v117, v120
	v_cndmask_b32_e64 v116, v183, 0, s[26:27]
	s_or_b64 s[26:27], s[0:1], s[94:95]
	v_mul_f32_e32 v141, v116, v117
	v_fmac_f32_e32 v2, v116, v117
	v_fma_f32 v117, v118, s62, v142
	v_exp_f32_e32 v117, v117
	v_cndmask_b32_e64 v116, v184, 0, s[26:27]
	s_or_b64 s[26:27], s[0:1], s[96:97]
	v_mul_f32_e32 v142, v116, v117
	v_fmac_f32_e32 v2, v116, v117
	v_fma_f32 v117, v119, s62, v143
	v_exp_f32_e32 v117, v117
	v_cndmask_b32_e64 v116, v185, 0, s[26:27]
	v_mul_f32_e32 v143, v116, v117
	v_fmac_f32_e32 v2, v116, v117
	v_fma_f32 v117, v100, s62, v144
	v_exp_f32_e32 v100, v117
	v_cndmask_b32_e64 v116, v186, 0, s[0:1]
	v_mul_f32_e32 v144, v116, v100
	v_fmac_f32_e32 v2, v116, v100
	v_fma_f32 v116, v101, s62, v145
	v_exp_f32_e32 v101, v116
	v_cndmask_b32_e64 v100, v187, 0, s[0:1]
	v_mul_f32_e32 v145, v100, v101
	v_fmac_f32_e32 v2, v100, v101
	v_cndmask_b32_e64 v100, v189, 0, s[0:1]
	v_mul_f32_e32 v146, v100, v3
	v_fmac_f32_e32 v2, v100, v3
	s_waitcnt lgkmcnt(0)
	v_fma_f32 v100, v103, s62, v147
	v_exp_f32_e32 v100, v100
	v_cndmask_b32_e64 v3, v203, 0, s[0:1]
	v_mul_f32_e32 v147, v3, v100
	v_fmac_f32_e32 v2, v3, v100

; template <int DQK, bool NA, bool SMAX, int LDV> ...
;     ...
;         if (NA && it >= 4) {
;           const int kr = rs + (it - 4);
;           const int ql = w * 32 + qt * 16 + fr, qr = r0 + (ql >> 6), qc = ql & 63;
;           const int rst = min(max(qr - 4, 0), 24);
;           const bool rowok = (kr >= rst) && (kr < rst + 8);
;           const int cst = min(max(qc - 8, 0), 48);
;           const int base = (kr - qr + 7) * 31 + 15 - qc;
;           float bv[4][4];
; #pragma unroll
;           for (int kt = 0; kt < 4; ++kt)
; #pragma unroll
;             for (int j = 0; j < 4; ++j) bv[kt][j] = rpbl[min(max(base + kt * 16 + fq * 4 + j, 0), 464)];
; #pragma unroll
;           for (int kt = 0; kt < 4; ++kt)
; #pragma unroll
;             for (int j = 0; j < 4; ++j) {
;               const int kc = kt * 16 + fq * 4 + j;
;               const float okf = (rowok && (kc >= cst) && (kc < cst + 16)) ? 1.f : 0.f;
;               const float pv = __builtin_amdgcn_exp2f(__builtin_fmaf(s[kt][qt][j], c1, bv[kt][j] - m0)) * okf;
;               s[kt][qt][j] = pv; sum += pv;
;             }
.LBB0_1085:
	s_movk_i32 s101, 0x100
	v_lshl_add_u32 v211, v208, 2, s101
	ds_read_b32 v0, v211 offset:41728
	ds_read_b32 v105, v211 offset:41732
	ds_read_b32 v3, v211 offset:41932
	ds_read_b32 v106, v211 offset:41736
	s_add_i32 s0, s19, s43
	s_add_i32 s0, s0, -3
	v_cmp_ge_i32_e32 vcc, s0, v164
	v_cmp_lt_i32_e64 s[0:1], s0, v163
	s_waitcnt lgkmcnt(3)
	ds_read_b32 v107, v211 offset:41740
	s_or_b64 s[0:1], s[0:1], vcc
	v_fmac_f32_e32 v0, 0x3e38aa3b, v144
	s_waitcnt lgkmcnt(3)
	s_or_b64 s[26:27], s[0:1], s[58:59]
	v_exp_f32_e32 v0, v0
	v_fmac_f32_e32 v105, 0x3e38aa3b, v145
	v_cndmask_b32_e64 v104, v0, 0, s[26:27]
	v_readlane_b32 s26, v248, 21
	v_exp_f32_e32 v131, v105
	v_readlane_b32 s27, v248, 22
	ds_read_b32 v108, v211 offset:41792
	s_or_b64 s[26:27], s[0:1], s[26:27]
	s_waitcnt lgkmcnt(2)
	v_mov_b32_e32 v0, v104
	v_cndmask_b32_e64 v105, v131, 0, s[26:27]
	v_fmac_f32_e32 v106, 0x3e38aa3b, v146
	v_add_f32_e32 v0, v0, v105
	v_exp_f32_e32 v131, v106
	ds_read_b32 v109, v211 offset:41796
	s_or_b64 s[26:27], s[0:1], s[52:53]
	s_waitcnt lgkmcnt(2)
	v_cndmask_b32_e64 v106, v131, 0, s[26:27]
	v_fmac_f32_e32 v107, 0x3e38aa3b, v147
	v_add_f32_e32 v0, v0, v106
	v_exp_f32_e32 v131, v107
	ds_read_b32 v110, v211 offset:41800
	s_or_b64 s[26:27], s[0:1], s[54:55]
	s_waitcnt lgkmcnt(2)
	v_cndmask_b32_e64 v107, v131, 0, s[26:27]
	v_fmac_f32_e32 v108, 0x3e38aa3b, v140
	v_add_f32_e32 v0, v0, v107
	v_exp_f32_e32 v131, v108
	ds_read_b32 v111, v211 offset:41804
	s_or_b64 s[26:27], s[0:1], s[56:57]
	s_waitcnt lgkmcnt(2)
	v_cndmask_b32_e64 v130, v165, 0, s[26:27]
	v_fmac_f32_e32 v109, 0x3e38aa3b, v141
	v_mul_f32_e32 v108, v130, v131
	v_fmac_f32_e32 v0, v130, v131
	v_exp_f32_e32 v131, v109
	ds_read_b32 v112, v211 offset:41856
	s_or_b64 s[26:27], s[0:1], s[60:61]
	s_waitcnt lgkmcnt(2)
	v_cndmask_b32_e64 v130, v166, 0, s[26:27]
	v_fmac_f32_e32 v110, 0x3e38aa3b, v142
	v_mul_f32_e32 v109, v130, v131
	v_fmac_f32_e32 v0, v130, v131
	v_exp_f32_e32 v131, v110
	ds_read_b32 v113, v211 offset:41860
	s_or_b64 s[26:27], s[0:1], s[50:51]
	s_waitcnt lgkmcnt(2)
	v_cndmask_b32_e64 v130, v168, 0, s[26:27]
	v_fmac_f32_e32 v111, 0x3e38aa3b, v143
	v_mul_f32_e32 v110, v130, v131
	v_fmac_f32_e32 v0, v130, v131
	v_exp_f32_e32 v131, v111
	ds_read_b32 v114, v211 offset:41864
	s_or_b64 s[26:27], s[0:1], s[64:65]
	s_waitcnt lgkmcnt(2)
	v_cndmask_b32_e64 v130, v169, 0, s[26:27]
	v_fmac_f32_e32 v112, 0x3e38aa3b, v136
	v_mul_f32_e32 v111, v130, v131
	v_fmac_f32_e32 v0, v130, v131
	v_exp_f32_e32 v131, v112
	ds_read_b32 v115, v211 offset:41868
	s_or_b64 s[26:27], s[0:1], s[66:67]
	s_waitcnt lgkmcnt(2)
	v_cndmask_b32_e64 v130, v170, 0, s[26:27]
	v_fmac_f32_e32 v113, 0x3e38aa3b, v137
	v_mul_f32_e32 v112, v130, v131
	v_fmac_f32_e32 v0, v130, v131
	v_exp_f32_e32 v131, v113
	ds_read_b32 v128, v211 offset:41920
	s_or_b64 s[26:27], s[0:1], s[68:69]
	s_waitcnt lgkmcnt(2)
	v_cndmask_b32_e64 v130, v171, 0, s[26:27]
	v_fmac_f32_e32 v114, 0x3e38aa3b, v138
	v_mul_f32_e32 v113, v130, v131
	v_fmac_f32_e32 v0, v130, v131
	v_exp_f32_e32 v131, v114
	ds_read_b32 v129, v211 offset:41924
	s_or_b64 s[26:27], s[0:1], s[70:71]
	s_waitcnt lgkmcnt(2)
	v_cndmask_b32_e64 v130, v172, 0, s[26:27]
	v_fmac_f32_e32 v115, 0x3e38aa3b, v139
	v_mul_f32_e32 v114, v130, v131
	v_fmac_f32_e32 v0, v130, v131
	v_exp_f32_e32 v131, v115
	ds_read_b32 v2, v211 offset:41928
	s_or_b64 s[26:27], s[0:1], s[72:73]
	s_waitcnt lgkmcnt(2)
	v_cndmask_b32_e64 v130, v173, 0, s[26:27]
	v_fmac_f32_e32 v128, 0x3e38aa3b, v132
	v_mul_f32_e32 v115, v130, v131
	v_fmac_f32_e32 v0, v130, v131
	v_exp_f32_e32 v131, v128
	s_waitcnt lgkmcnt(1)
	v_cndmask_b32_e64 v130, v174, 0, s[0:1]
	v_fmac_f32_e32 v129, 0x3e38aa3b, v133
	s_waitcnt lgkmcnt(0)
	v_mul_f32_e32 v128, v130, v131
	v_fmac_f32_e32 v0, v130, v131
	v_exp_f32_e32 v131, v129
	v_fmac_f32_e32 v2, 0x3e38aa3b, v134
	v_exp_f32_e32 v2, v2
	v_fmac_f32_e32 v3, 0x3e38aa3b, v135
	v_exp_f32_e32 v3, v3
	v_cndmask_b32_e64 v130, v175, 0, s[0:1]
	v_mul_f32_e32 v129, v130, v131
	v_fmac_f32_e32 v0, v130, v131
	v_cndmask_b32_e64 v131, v176, 0, s[0:1]
	v_mul_f32_e32 v130, v131, v2
	v_fmac_f32_e32 v0, v131, v2
	v_cndmask_b32_e64 v2, v177, 0, s[0:1]
	v_mul_f32_e32 v131, v2, v3
	v_fmac_f32_e32 v0, v2, v3

; template <int DQK, bool NA, bool SMAX, int LDV> ...
;     ...
;         if (NA && it >= 4) {
;           const int kr = rs + (it - 4);
;           const int ql = w * 32 + qt * 16 + fr, qr = r0 + (ql >> 6), qc = ql & 63;
;           const int rst = min(max(qr - 4, 0), 24);
;           const bool rowok = (kr >= rst) && (kr < rst + 8);
;           const int cst = min(max(qc - 8, 0), 48);
;           const int base = (kr - qr + 7) * 31 + 15 - qc;
;           float bv[4][4];
; #pragma unroll
;           for (int kt = 0; kt < 4; ++kt)
; #pragma unroll
;             for (int j = 0; j < 4; ++j) bv[kt][j] = rpbl[min(max(base + kt * 16 + fq * 4 + j, 0), 464)];
; #pragma unroll
;           for (int kt = 0; kt < 4; ++kt)
; #pragma unroll
;             for (int j = 0; j < 4; ++j) {
;               const int kc = kt * 16 + fq * 4 + j;
;               const float okf = (rowok && (kc >= cst) && (kc < cst + 16)) ? 1.f : 0.f;
;               const float pv = __builtin_amdgcn_exp2f(__builtin_fmaf(s[kt][qt][j], c1, bv[kt][j] - m0)) * okf;
;               s[kt][qt][j] = pv; sum += pv;
;             }
.LBB0_1089:
	v_add_u32_e32 v2, -16, v208
	s_movk_i32 s101, 0x100
	v_lshl_add_u32 v211, v2, 2, s101
	ds_read_b32 v132, v211 offset:41728
	ds_read_b32 v133, v211 offset:41732
	ds_read_b32 v134, v211 offset:41736
	ds_read_b32 v135, v211 offset:41740
	ds_read_b32 v136, v211 offset:41792
	ds_read_b32 v137, v211 offset:41796
	ds_read_b32 v138, v211 offset:41800
	ds_read_b32 v139, v211 offset:41804
	ds_read_b32 v140, v211 offset:41856
	ds_read_b32 v141, v211 offset:41860
	ds_read_b32 v142, v211 offset:41864
	ds_read_b32 v143, v211 offset:41868
	ds_read_b32 v144, v211 offset:41920
	s_add_i32 s0, s19, s43
	s_waitcnt lgkmcnt(12)
	s_add_i32 s0, s0, -3
	ds_read_b32 v145, v211 offset:41924
	v_fmac_f32_e32 v132, 0x3e38aa3b, v124
	s_waitcnt lgkmcnt(12)
	v_cmp_ge_i32_e32 vcc, s0, v164
	v_cmp_lt_i32_e64 s[0:1], s0, v163
	v_exp_f32_e32 v124, v132
	v_fmac_f32_e32 v133, 0x3e38aa3b, v125
	s_or_b64 s[0:1], s[0:1], vcc
	v_exp_f32_e32 v125, v133
	s_or_b64 s[26:27], s[0:1], s[82:83]
	ds_read_b32 v3, v211 offset:41928
	ds_read_b32 v147, v211 offset:41932
	v_cndmask_b32_e64 v132, v124, 0, s[26:27]
	s_or_b64 s[26:27], s[0:1], s[74:75]
	v_mov_b32_e32 v2, v132
	v_cndmask_b32_e64 v133, v125, 0, s[26:27]
	v_add_f32_e32 v2, v2, v133
	s_waitcnt lgkmcnt(13)
	v_fma_f32 v125, v126, s62, v134
	v_exp_f32_e32 v125, v125
	s_or_b64 s[26:27], s[0:1], s[76:77]
	v_cndmask_b32_e64 v134, v125, 0, s[26:27]
	s_or_b64 s[26:27], s[0:1], s[78:79]
	v_add_f32_e32 v2, v2, v134
	s_waitcnt lgkmcnt(12)
	v_fma_f32 v125, v127, s62, v135
	v_exp_f32_e32 v125, v125
	s_nop 0
	v_cndmask_b32_e64 v135, v125, 0, s[26:27]
	s_or_b64 s[26:27], s[0:1], s[80:81]
	s_waitcnt lgkmcnt(1)
	v_add_f32_e32 v2, v2, v135
	v_fma_f32 v125, v120, s62, v136
	v_exp_f32_e32 v120, v125
	v_cndmask_b32_e64 v124, v178, 0, s[26:27]
	s_or_b64 s[26:27], s[0:1], s[84:85]
	v_fmac_f32_e32 v3, 0x3e38aa3b, v102
	v_mul_f32_e32 v136, v124, v120
	v_fmac_f32_e32 v2, v124, v120
	v_fma_f32 v124, v121, s62, v137
	v_exp_f32_e32 v121, v124
	v_cndmask_b32_e64 v120, v179, 0, s[26:27]
	s_or_b64 s[26:27], s[0:1], s[86:87]
	v_exp_f32_e32 v3, v3
	v_mul_f32_e32 v137, v120, v121
	v_fmac_f32_e32 v2, v120, v121
	v_fma_f32 v121, v122, s62, v138
	v_exp_f32_e32 v121, v121
	v_cndmask_b32_e64 v120, v180, 0, s[26:27]
	s_or_b64 s[26:27], s[0:1], s[88:89]
	v_mul_f32_e32 v138, v120, v121
	v_fmac_f32_e32 v2, v120, v121
	v_fma_f32 v121, v123, s62, v139
	v_exp_f32_e32 v121, v121
	v_cndmask_b32_e64 v120, v181, 0, s[26:27]
	s_or_b64 s[26:27], s[0:1], s[90:91]
	v_mul_f32_e32 v139, v120, v121
	v_fmac_f32_e32 v2, v120, v121
	v_fma_f32 v121, v116, s62, v140
	v_exp_f32_e32 v116, v121
	v_cndmask_b32_e64 v120, v182, 0, s[26:27]
	s_or_b64 s[26:27], s[0:1], s[92:93]
	v_mul_f32_e32 v140, v120, v116
	v_fmac_f32_e32 v2, v120, v116
	v_fma_f32 v120, v117, s62, v141
	v_exp_f32_e32 v117, v120
	v_cndmask_b32_e64 v116, v183, 0, s[26:27]
	s_or_b64 s[26:27], s[0:1], s[94:95]
	v_mul_f32_e32 v141, v116, v117
	v_fmac_f32_e32 v2, v116, v117
	v_fma_f32 v117, v118, s62, v142
	v_exp_f32_e32 v117, v117
	v_cndmask_b32_e64 v116, v184, 0, s[26:27]
	s_or_b64 s[26:27], s[0:1], s[96:97]
	v_mul_f32_e32 v142, v116, v117
	v_fmac_f32_e32 v2, v116, v117
	v_fma_f32 v117, v119, s62, v143
	v_exp_f32_e32 v117, v117
	v_cndmask_b32_e64 v116, v185, 0, s[26:27]
	v_mul_f32_e32 v143, v116, v117
	v_fmac_f32_e32 v2, v116, v117
	v_fma_f32 v117, v100, s62, v144
	v_exp_f32_e32 v100, v117
	v_cndmask_b32_e64 v116, v186, 0, s[0:1]
	v_mul_f32_e32 v144, v116, v100
	v_fmac_f32_e32 v2, v116, v100
	v_fma_f32 v116, v101, s62, v145
	v_exp_f32_e32 v101, v116
	v_cndmask_b32_e64 v100, v187, 0, s[0:1]
	v_mul_f32_e32 v145, v100, v101
	v_fmac_f32_e32 v2, v100, v101
	v_cndmask_b32_e64 v100, v189, 0, s[0:1]
	v_mul_f32_e32 v146, v100, v3
	v_fmac_f32_e32 v2, v100, v3
	s_waitcnt lgkmcnt(0)
	v_fma_f32 v100, v103, s62, v147
	v_exp_f32_e32 v100, v100
	v_cndmask_b32_e64 v3, v203, 0, s[0:1]
	v_mul_f32_e32 v147, v3, v100
	v_fmac_f32_e32 v2, v3, v100
